# C1: tile r|k|v loads requested before the last weight group (land under group 3 + staging barrier + read-back); C2 row slots rotated so the 32 workgroups with a fifth C1 tile take 8-row slots
# speedup vs baseline: 1.0269x; 1.0004x over previous
; __device__ __forceinline__ float bf2f(bf16_t b) { return __uint_as_float((unsigned)b << 16); }
; __device__ __forceinline__ unsigned cvtpk(float lo, float hi) { unsigned r; asm volatile("v_cvt_pk_bf16_f32 %0, %1, %2" : "=v"(r) : "v"(lo), "v"(hi)); return r; }
; __global__ void __launch_bounds__(NWAVES * 64, 2) mk_fwd(Args args) {
;     ...
;                     __syncthreads();
; #pragma unroll
;                     for (int e = 0; e < 4; ++e) { const int idx = tid + 512 * e, tok = idx >> 7, i = idx & 127, col = 3072 + i, m = m0 + tok;
;                         const float cur = bf2f(proj[(size_t)m * NPAD + col]);
;                         float prev;
;                         if (tok == 0 && first) prev = smp ? shst[col] : 0.f; else prev = bf2f(proj[(size_t)(m - 1) * NPAD + col]);
;                         float xsv = cur + (prev - cur) * mu[col];
;                         if (i < 64) { const float e2 = __expf(2.f * xsv); xsv = 1.f - 2.f * __builtin_amdgcn_rcpf(e2 + 1.f); }
;                         const float xo = __shfl_xor(xsv, 1);
;                         if (!(i & 1)) actP[(i >> 1) * 16 + tok] = cvtpk(xsv, xo); }
;     ...
;                     u32x2 wvn = *(const u32x2*)(w2pl + c0), avn = *(const u32x2*)(w2pl + (size_t)32 * RW + c0);
;                     for (int ip = 0; ip < 32; ++ip) {
;                         const u32x2 wv = wvn, av = avn;
;                         { const int ipn = ip < 31 ? ip + 1 : 31; wvn = *(const u32x2*)(w2pl + (size_t)ipn * RW + c0); avn = *(const u32x2*)(w2pl + (size_t)(32 + ipn) * RW + c0); }
.LBB0_434:
	s_or_b64 exec, exec, s[58:59]
	v_and_b32_e32 v248, 15, v109
	v_bfe_u32 v20, v109, 4, 2
	v_lshlrev_b32_e32 v248, 4, v248
	v_lshl_or_b32 v248, v20, 14, v248
	s_mov_b64 s[94:95], s[92:93]
	global_load_dwordx4 v[28:31], v248, s[94:95]
	s_add_u32 s94, s92, 0x1000
	s_addc_u32 s95, s93, 0
	global_load_dwordx4 v[32:35], v248, s[94:95]
	s_add_u32 s94, s92, 0x2000
	s_addc_u32 s95, s93, 0
	global_load_dwordx4 v[74:77], v248, s[94:95]
	s_add_u32 s94, s92, 0x3000
	s_addc_u32 s95, s93, 0
	global_load_dwordx4 v[132:135], v248, s[94:95]
	s_add_u32 s94, s92, 0x10000
	s_addc_u32 s95, s93, 0
	global_load_dwordx4 v[176:179], v248, s[94:95]
	s_add_u32 s94, s92, 0x11000
	s_addc_u32 s95, s93, 0
	global_load_dwordx4 v[228:231], v248, s[94:95]
	s_add_u32 s94, s92, 0x12000
	s_addc_u32 s95, s93, 0
	global_load_dwordx4 v[240:243], v248, s[94:95]
	s_add_u32 s94, s92, 0x13000
	s_addc_u32 s95, s93, 0
	global_load_dwordx4 v[244:247], v248, s[94:95]
	s_mov_b64 s[94:95], s[92:93]
	global_load_dwordx4 v[160:163], v248, s[94:95] offset:256
	s_add_u32 s94, s92, 0x1000
	s_addc_u32 s95, s93, 0
	global_load_dwordx4 v[172:175], v248, s[94:95] offset:256
	s_add_u32 s94, s92, 0x2000
	s_addc_u32 s95, s93, 0
	global_load_dwordx4 v[180:183], v248, s[94:95] offset:256
	s_add_u32 s94, s92, 0x3000
	s_addc_u32 s95, s93, 0
	global_load_dwordx4 v[184:187], v248, s[94:95] offset:256
	s_add_u32 s94, s92, 0x10000
	s_addc_u32 s95, s93, 0
	global_load_dwordx4 v[208:211], v248, s[94:95] offset:256
	s_add_u32 s94, s92, 0x11000
	s_addc_u32 s95, s93, 0
	global_load_dwordx4 v[212:215], v248, s[94:95] offset:256
	s_add_u32 s94, s92, 0x12000
	s_addc_u32 s95, s93, 0
	global_load_dwordx4 v[216:219], v248, s[94:95] offset:256
	s_add_u32 s94, s92, 0x13000
	s_addc_u32 s95, s93, 0
	global_load_dwordx4 v[220:223], v248, s[94:95] offset:256
	s_add_u32 s94, s92, 0x20000
	s_addc_u32 s95, s93, 0
	global_load_dwordx4 v[128:131], v248, s[94:95]
	s_add_u32 s94, s92, 0x21000
	s_addc_u32 s95, s93, 0
	global_load_dwordx4 v[136:139], v248, s[94:95]
	s_add_u32 s94, s92, 0x22000
	s_addc_u32 s95, s93, 0
	global_load_dwordx4 v[140:143], v248, s[94:95]
	s_add_u32 s94, s92, 0x23000
	s_addc_u32 s95, s93, 0
	global_load_dwordx4 v[144:147], v248, s[94:95]
	s_add_u32 s94, s92, 0x30000
	s_addc_u32 s95, s93, 0
	global_load_dwordx4 v[148:151], v248, s[94:95]
	s_add_u32 s94, s92, 0x31000
	s_addc_u32 s95, s93, 0
	global_load_dwordx4 v[152:155], v248, s[94:95]
	s_add_u32 s94, s92, 0x32000
	s_addc_u32 s95, s93, 0
	global_load_dwordx4 v[156:159], v248, s[94:95]
	s_add_u32 s94, s92, 0x33000
	s_addc_u32 s95, s93, 0
	global_load_dwordx4 v[232:235], v248, s[94:95]
	v_and_b32_e32 v20, 0x7e, v109
	v_lshlrev_b32_e32 v20, 1, v20
	v_mul_u32_u24_e32 v8, 0x110, v55
	v_add_u32_e32 v20, v20, v8
	v_add_u32_e32 v20, 0x22400, v20
	s_waitcnt vmcnt(24)
	s_barrier
	v_lshlrev_b32_e32 v16, 16, v16
	v_cndmask_b32_e64 v16, v7, v16, s[58:59]
	v_lshlrev_b32_e32 v17, 16, v17
	v_lshlrev_b32_e32 v18, 16, v18
	v_lshlrev_b32_e32 v19, 16, v19
	v_lshlrev_b32_e32 v12, 16, v12
	v_lshlrev_b32_e32 v13, 16, v13
	v_lshlrev_b32_e32 v14, 16, v14
	v_lshlrev_b32_e32 v15, 16, v15
	v_sub_f32_e32 v16, v16, v12
	v_sub_f32_e32 v17, v17, v13
	v_sub_f32_e32 v18, v18, v14
	v_sub_f32_e32 v19, v19, v15
	v_fmac_f32_e32 v12, v16, v9
	v_fmac_f32_e32 v13, v17, v9
	v_fmac_f32_e32 v14, v18, v9
	v_fmac_f32_e32 v15, v19, v9
	v_add_f32_e32 v16, v12, v12
	v_add_f32_e32 v17, v13, v13
	v_add_f32_e32 v18, v14, v14
	v_add_f32_e32 v19, v15, v15
	v_mul_f32_e32 v16, 0x3fb8aa3b, v16
	v_mul_f32_e32 v17, 0x3fb8aa3b, v17
	v_mul_f32_e32 v18, 0x3fb8aa3b, v18
	v_mul_f32_e32 v19, 0x3fb8aa3b, v19
	v_exp_f32_e32 v16, v16
	v_exp_f32_e32 v17, v17
	v_exp_f32_e32 v18, v18
	v_exp_f32_e32 v19, v19
	s_nop 0
	v_add_f32_e32 v16, 1.0, v16
	v_add_f32_e32 v17, 1.0, v17
	v_add_f32_e32 v18, 1.0, v18
	v_add_f32_e32 v19, 1.0, v19
	v_rcp_f32_e32 v16, v16
	v_rcp_f32_e32 v17, v17
	v_rcp_f32_e32 v18, v18
	v_rcp_f32_e32 v19, v19
	s_nop 0
	v_fma_f32 v16, v16, -2.0, 1.0
	v_fma_f32 v17, v17, -2.0, 1.0
	v_fma_f32 v18, v18, -2.0, 1.0
	v_fma_f32 v19, v19, -2.0, 1.0
	v_cndmask_b32_e64 v12, v12, v16, s[2:3]
	v_cndmask_b32_e64 v13, v13, v17, s[2:3]
	v_cndmask_b32_e64 v14, v14, v18, s[2:3]
	v_cndmask_b32_e64 v15, v15, v19, s[2:3]
	ds_bpermute_b32 v16, v88, v12
	ds_bpermute_b32 v17, v88, v13
	ds_bpermute_b32 v18, v88, v14
	ds_bpermute_b32 v19, v88, v15
	s_and_saveexec_b64 s[56:57], s[4:5]
	s_waitcnt lgkmcnt(0)
	v_cvt_pk_bf16_f32 v12, v12, v16
	ds_write_b32 v20, v12 offset:0
	v_cvt_pk_bf16_f32 v13, v13, v17
	ds_write_b32 v20, v13 offset:1088
	v_cvt_pk_bf16_f32 v14, v14, v18
	ds_write_b32 v20, v14 offset:2176
	v_cvt_pk_bf16_f32 v15, v15, v19
	ds_write_b32 v20, v15 offset:3264
; #define LAS __attribute__((address_space(3)))
; #define DOT2(a_, b_, c_) __builtin_amdgcn_fdot2_f32_bf16(__builtin_bit_cast(bf16x2_t, (unsigned)(a_)), __builtin_bit_cast(bf16x2_t, (unsigned)(b_)), (c_), false)
; __global__ void __launch_bounds__(NWAVES * 64, 2) mk_fwd(Args args) {
;     ...
;                     for (int ip = 0; ip < 32; ++ip) {
;                         const u32x2 wv = wvn, av = avn;
;                         { const int ipn = ip < 31 ? ip + 1 : 31; wvn = *(const u32x2*)(w2pl + (size_t)ipn * RW + c0); avn = *(const u32x2*)(w2pl + (size_t)(32 + ipn) * RW + c0); }
; #pragma unroll
;                         for (int tq = 0; tq < 4; ++tq) { const u32x4 x4 = *(LAS const u32x4*)(actP + ip * 16 + tq * 4), y4 = *(LAS const u32x4*)(actP + (32 + ip) * 16 + tq * 4);
; #pragma unroll
;                             for (int e = 0; e < 4; ++e) { lw[tq * 4 + e][0] = DOT2(x4[e], wv.x, lw[tq * 4 + e][0]); lw[tq * 4 + e][1] = DOT2(x4[e], wv.y, lw[tq * 4 + e][1]);
;                                                           la[tq * 4 + e][0] = DOT2(y4[e], av.x, la[tq * 4 + e][0]); la[tq * 4 + e][1] = DOT2(y4[e], av.y, la[tq * 4 + e][1]); } }
;                     }
.LBB0_457:
	s_or_b64 exec, exec, s[56:57]
	s_waitcnt lgkmcnt(0)
	s_barrier
	v_and_b32_e32 v249, 15, v109
	v_mul_u32_u24_e32 v249, 0x110, v249
	v_bfe_u32 v164, v109, 4, 2
	v_lshl_add_u32 v249, v164, 4, v249
	v_add_u32_e32 v249, 0x22400, v249
	ds_read_b128 v[20:23], v249 offset:0
	ds_read_b128 v[24:27], v249 offset:64
	v_lshrrev_b32_e32 v164, 6, v109
	v_lshl_add_u32 v164, v164, 9, v248
	v_add_u32_e32 v165, 0x10000, v164
	v_lshlrev_b32_e32 v194, 3, v109
	v_add_u32_e32 v195, 0x10000, v194
	s_waitcnt vmcnt(16)
	v_swap_b32 v29, v32
	v_swap_b32 v30, v74
	v_swap_b32 v31, v132
	v_swap_b32 v34, v75
	v_swap_b32 v35, v133
	v_swap_b32 v77, v134
	v_swap_b32 v177, v228
	v_swap_b32 v178, v240
	v_swap_b32 v179, v244
	v_swap_b32 v230, v241
	v_swap_b32 v231, v245
	v_swap_b32 v243, v246
	s_waitcnt lgkmcnt(0)
	s_nop 1
	v_mfma_f32_16x16x32_bf16 v[4:7], v[20:23], v[28:31], 0
	v_mfma_f32_16x16x32_bf16 v[8:11], v[20:23], v[32:35], 0
	v_mfma_f32_16x16x32_bf16 v[12:15], v[20:23], v[74:77], 0
	v_mfma_f32_16x16x32_bf16 v[16:19], v[20:23], v[132:135], 0
	v_mfma_f32_16x16x32_bf16 v[4:7], v[24:27], v[176:179], v[4:7]
	v_mfma_f32_16x16x32_bf16 v[8:11], v[24:27], v[228:231], v[8:11]
	v_mfma_f32_16x16x32_bf16 v[12:15], v[24:27], v[240:243], v[12:15]
	v_mfma_f32_16x16x32_bf16 v[16:19], v[24:27], v[244:247], v[16:19]
	s_add_u32 s94, s92, 0x20000
	s_addc_u32 s95, s93, 0
	global_load_dwordx4 v[28:31], v248, s[94:95] offset:256
	s_add_u32 s94, s92, 0x21000
	s_addc_u32 s95, s93, 0
	global_load_dwordx4 v[32:35], v248, s[94:95] offset:256
	s_add_u32 s94, s92, 0x22000
	s_addc_u32 s95, s93, 0
	global_load_dwordx4 v[74:77], v248, s[94:95] offset:256
	s_add_u32 s94, s92, 0x23000
	s_addc_u32 s95, s93, 0
	global_load_dwordx4 v[132:135], v248, s[94:95] offset:256
	s_add_u32 s94, s92, 0x30000
	s_addc_u32 s95, s93, 0
	global_load_dwordx4 v[176:179], v248, s[94:95] offset:256
	s_add_u32 s94, s92, 0x31000
	s_addc_u32 s95, s93, 0
	global_load_dwordx4 v[228:231], v248, s[94:95] offset:256
	s_add_u32 s94, s92, 0x32000
	s_addc_u32 s95, s93, 0
	global_load_dwordx4 v[240:243], v248, s[94:95] offset:256
	s_add_u32 s94, s92, 0x33000
	s_addc_u32 s95, s93, 0
	global_load_dwordx4 v[244:247], v248, s[94:95] offset:256
	s_waitcnt vmcnt(16)
	v_swap_b32 v161, v172
	v_swap_b32 v162, v180
	v_swap_b32 v163, v184
	v_swap_b32 v174, v181
	v_swap_b32 v175, v185
	v_swap_b32 v183, v186
	v_swap_b32 v209, v212
	v_swap_b32 v210, v216
	v_swap_b32 v211, v220
	v_swap_b32 v214, v217
	v_swap_b32 v215, v221
	v_swap_b32 v219, v222
	s_nop 1
	v_mfma_f32_16x16x32_bf16 v[100:103], v[20:23], v[160:163], 0
	v_mfma_f32_16x16x32_bf16 v[104:107], v[20:23], v[172:175], 0
	v_mfma_f32_16x16x32_bf16 v[112:115], v[20:23], v[180:183], 0
	v_mfma_f32_16x16x32_bf16 v[116:119], v[20:23], v[184:187], 0
	v_mfma_f32_16x16x32_bf16 v[100:103], v[24:27], v[208:211], v[100:103]
	v_mfma_f32_16x16x32_bf16 v[104:107], v[24:27], v[212:215], v[104:107]
	v_mfma_f32_16x16x32_bf16 v[112:115], v[24:27], v[216:219], v[112:115]
	v_mfma_f32_16x16x32_bf16 v[116:119], v[24:27], v[220:223], v[116:119]
	ds_read_b128 v[20:23], v249 offset:128
	ds_read_b128 v[24:27], v249 offset:192
	v_swap_b32 v5, v8
	v_swap_b32 v6, v12
	v_swap_b32 v7, v16
	v_swap_b32 v10, v13
	v_swap_b32 v11, v17
	v_swap_b32 v15, v18
	ds_write_b128 v164, v[4:7] offset:0
	ds_write_b128 v164, v[8:11] offset:4096
	ds_write_b128 v164, v[12:15] offset:8192
	ds_write_b128 v164, v[16:19] offset:12288
	s_waitcnt vmcnt(8)
	v_swap_b32 v129, v136
	v_swap_b32 v130, v140
	v_swap_b32 v131, v144
	v_swap_b32 v138, v141
	v_swap_b32 v139, v145
	v_swap_b32 v143, v146
	v_swap_b32 v149, v152
	v_swap_b32 v150, v156
	v_swap_b32 v151, v232
	v_swap_b32 v154, v157
	v_swap_b32 v155, v233
	v_swap_b32 v159, v234
	s_waitcnt lgkmcnt(4)
	s_nop 1
	v_mfma_f32_16x16x32_bf16 v[4:7], v[20:23], v[128:131], 0
	v_mfma_f32_16x16x32_bf16 v[8:11], v[20:23], v[136:139], 0
	v_mfma_f32_16x16x32_bf16 v[12:15], v[20:23], v[140:143], 0
	v_mfma_f32_16x16x32_bf16 v[16:19], v[20:23], v[144:147], 0
	v_mfma_f32_16x16x32_bf16 v[4:7], v[24:27], v[148:151], v[4:7]
	v_mfma_f32_16x16x32_bf16 v[8:11], v[24:27], v[152:155], v[8:11]
	v_mfma_f32_16x16x32_bf16 v[12:15], v[24:27], v[156:159], v[12:15]
	v_mfma_f32_16x16x32_bf16 v[16:19], v[24:27], v[232:235], v[16:19]
	v_swap_b32 v101, v104
	v_swap_b32 v102, v112
	v_swap_b32 v103, v116
	v_swap_b32 v106, v113
	v_swap_b32 v107, v117
	v_swap_b32 v115, v118
	ds_write_b128 v164, v[100:103] offset:256
	ds_write_b128 v164, v[104:107] offset:4352
	ds_write_b128 v164, v[112:115] offset:8448
	ds_write_b128 v164, v[116:119] offset:12544
	s_nop 7
	v_swap_b32 v5, v8
	v_swap_b32 v6, v12
	v_swap_b32 v7, v16
	v_swap_b32 v10, v13
	v_swap_b32 v11, v17
	v_swap_b32 v15, v18
	ds_write_b128 v165, v[4:7] offset:0
	ds_write_b128 v165, v[8:11] offset:4096
	ds_write_b128 v165, v[12:15] offset:8192
	ds_write_b128 v165, v[16:19] offset:12288
	v_mov_b32_e32 v122, 0
	v_mov_b32_e32 v227, 0
	v_mov_b32_e32 v80, 0
	v_mov_b32_e32 v81, 0
	s_andn2_b64 vcc, exec, s[88:89]
	s_cbranch_vccnz .LBB0_459
	s_add_i32 s56, s80, -1
	v_mad_i64_i32 v[4:5], s[56:57], s56, v198, v[60:61]
	global_load_dword v81, v[4:5], off
	global_load_dword v80, v[4:5], off offset:2048
	v_add_co_u32_e32 v4, vcc, 0x1000, v4
	s_nop 1
	v_addc_co_u32_e32 v5, vcc, 0, v5, vcc
	global_load_dword v227, v[4:5], off
; #define LAS __attribute__((address_space(3)))
; #define DOT2(a_, b_, c_) __builtin_amdgcn_fdot2_f32_bf16(__builtin_bit_cast(bf16x2_t, (unsigned)(a_)), __builtin_bit_cast(bf16x2_t, (unsigned)(b_)), (c_), false)
; __global__ void __launch_bounds__(NWAVES * 64, 2) mk_fwd(Args args) {
;     ...
;                     unsigned pur[17], puk[17], puv[17];
; #pragma unroll
;                     for (int tok = 0; tok < 17; ++tok) { if (tok == 0 && first) { pur[0] = puk[0] = puv[0] = 0u; continue; }
;                         const bf16_t* pp = proj + (size_t)(m0 + tok - 1) * NPAD + c0; pur[tok] = *(const unsigned*)pp; puk[tok] = *(const unsigned*)(pp + RW); puv[tok] = *(const unsigned*)(pp + 2 * RW); }
;     ...
;                     for (int ip = 0; ip < 32; ++ip) {
;                         const u32x2 wv = wvn, av = avn;
;                         { const int ipn = ip < 31 ? ip + 1 : 31; wvn = *(const u32x2*)(w2pl + (size_t)ipn * RW + c0); avn = *(const u32x2*)(w2pl + (size_t)(32 + ipn) * RW + c0); }
; #pragma unroll
;                         for (int tq = 0; tq < 4; ++tq) { const u32x4 x4 = *(LAS const u32x4*)(actP + ip * 16 + tq * 4), y4 = *(LAS const u32x4*)(actP + (32 + ip) * 16 + tq * 4);
; #pragma unroll
;                             for (int e = 0; e < 4; ++e) { lw[tq * 4 + e][0] = DOT2(x4[e], wv.x, lw[tq * 4 + e][0]); lw[tq * 4 + e][1] = DOT2(x4[e], wv.y, lw[tq * 4 + e][1]);
;                                                           la[tq * 4 + e][0] = DOT2(y4[e], av.x, la[tq * 4 + e][0]); la[tq * 4 + e][1] = DOT2(y4[e], av.y, la[tq * 4 + e][1]); } }
;                     }
.LBB0_459:
	v_mad_i64_i32 v[4:5], s[56:57], s80, v198, v[60:61]
	v_add_co_u32_e32 v6, vcc, 0x1000, v4
	s_or_b32 s90, s80, 1
	s_nop 0
	v_addc_co_u32_e32 v7, vcc, 0, v5, vcc
	v_mad_i64_i32 v[8:9], s[56:57], s90, v198, v[60:61]
	v_add_co_u32_e32 v10, vcc, 0x1000, v8
	s_or_b32 s86, s80, 2
	s_nop 0
	v_addc_co_u32_e32 v11, vcc, 0, v9, vcc
	v_mad_i64_i32 v[12:13], s[56:57], s86, v198, v[60:61]
	v_add_co_u32_e32 v14, vcc, 0x1000, v12
	s_or_b32 s82, s80, 3
	s_nop 0
	v_addc_co_u32_e32 v15, vcc, 0, v13, vcc
	v_mad_i64_i32 v[16:17], s[56:57], s82, v198, v[60:61]
	global_load_dword v224, v[6:7], off
	global_load_dword v221, v[8:9], off
	global_load_dword v220, v[8:9], off offset:2048
	global_load_dword v216, v[10:11], off
	global_load_dword v214, v[12:13], off
	global_load_dword v213, v[12:13], off offset:2048
	global_load_dword v210, v[14:15], off
	global_load_dword v206, v[16:17], off
	v_add_co_u32_e32 v6, vcc, 0x1000, v16
	s_or_b32 s78, s80, 4
	s_nop 0
	v_addc_co_u32_e32 v7, vcc, 0, v17, vcc
	v_mad_i64_i32 v[8:9], s[56:57], s78, v198, v[60:61]
	v_add_co_u32_e32 v10, vcc, 0x1000, v8
	s_or_b32 s76, s80, 5
	s_nop 0
	v_addc_co_u32_e32 v11, vcc, 0, v9, vcc
	v_mad_i64_i32 v[12:13], s[56:57], s76, v198, v[60:61]
	v_add_co_u32_e32 v14, vcc, 0x1000, v12
	s_or_b32 s74, s80, 6
	s_nop 0
	v_addc_co_u32_e32 v15, vcc, 0, v13, vcc
	global_load_dword v207, v[16:17], off offset:2048
	global_load_dword v187, v[6:7], off
	global_load_dword v182, v[8:9], off
	global_load_dword v181, v[8:9], off offset:2048
	global_load_dword v180, v[10:11], off
	global_load_dword v175, v[12:13], off
	global_load_dword v174, v[12:13], off offset:2048
	global_load_dword v173, v[14:15], off
	v_mad_i64_i32 v[6:7], s[56:57], s74, v198, v[60:61]
	v_add_co_u32_e32 v8, vcc, 0x1000, v6
	s_or_b32 s72, s80, 7
	s_nop 0
	v_addc_co_u32_e32 v9, vcc, 0, v7, vcc
	v_mad_i64_i32 v[10:11], s[56:57], s72, v198, v[60:61]
	v_add_co_u32_e32 v12, vcc, 0x1000, v10
	s_or_b32 s70, s80, 8
	s_nop 0
	v_addc_co_u32_e32 v13, vcc, 0, v11, vcc
	v_mad_i64_i32 v[14:15], s[56:57], s70, v198, v[60:61]
	global_load_dword v162, v[6:7], off
	global_load_dword v161, v[6:7], off offset:2048
	global_load_dword v158, v[8:9], off
	global_load_dword v156, v[10:11], off
	global_load_dword v155, v[10:11], off offset:2048
	global_load_dword v151, v[12:13], off
	global_load_dword v148, v[14:15], off
	global_load_dword v147, v[14:15], off offset:2048
	v_add_co_u32_e32 v6, vcc, 0x1000, v14
	s_or_b32 s68, s80, 9
	s_nop 0
	v_addc_co_u32_e32 v7, vcc, 0, v15, vcc
	v_mad_i64_i32 v[8:9], s[56:57], s68, v198, v[60:61]
	v_add_co_u32_e32 v10, vcc, 0x1000, v8
	s_or_b32 s66, s80, 10
	s_nop 0
	v_addc_co_u32_e32 v11, vcc, 0, v9, vcc
	v_mad_i64_i32 v[12:13], s[56:57], s66, v198, v[60:61]
	v_add_co_u32_e32 v14, vcc, 0x1000, v12
	s_or_b32 s64, s80, 11
	s_nop 0
	v_addc_co_u32_e32 v15, vcc, 0, v13, vcc
	v_mad_i64_i32 v[16:17], s[56:57], s64, v198, v[60:61]
	global_load_dword v144, v[6:7], off
	global_load_dword v143, v[8:9], off
	global_load_dword v142, v[8:9], off offset:2048
	global_load_dword v138, v[10:11], off
	global_load_dword v137, v[12:13], off
	global_load_dword v136, v[12:13], off offset:2048
	global_load_dword v131, v[14:15], off
	global_load_dword v129, v[16:17], off
	v_add_co_u32_e32 v6, vcc, 0x1000, v16
	s_or_b32 s62, s80, 12
	s_nop 0
	v_addc_co_u32_e32 v7, vcc, 0, v17, vcc
	v_mad_i64_i32 v[8:9], s[56:57], s62, v198, v[60:61]
	v_add_co_u32_e32 v10, vcc, 0x1000, v8
	s_or_b32 s60, s80, 13
	s_nop 0
	v_addc_co_u32_e32 v11, vcc, 0, v9, vcc
	v_mad_i64_i32 v[12:13], s[56:57], s60, v198, v[60:61]
	v_add_co_u32_e32 v14, vcc, 0x1000, v12
	s_or_b32 s58, s80, 14
	s_nop 0
	v_addc_co_u32_e32 v15, vcc, 0, v13, vcc
	global_load_dword v130, v[16:17], off offset:2048
	global_load_dword v125, v[6:7], off
	global_load_dword v121, v[8:9], off
	global_load_dword v120, v[8:9], off offset:2048
	global_load_dword v117, v[10:11], off
	global_load_dword v114, v[12:13], off
	global_load_dword v113, v[12:13], off offset:2048
	global_load_dword v110, v[14:15], off
	v_mad_i64_i32 v[6:7], s[56:57], s58, v198, v[60:61]
	v_add_co_u32_e32 v8, vcc, 0x1000, v6
	s_or_b32 s56, s80, 15
	s_nop 0
	v_addc_co_u32_e32 v9, vcc, 0, v7, vcc
	v_mad_i64_i32 v[10:11], vcc, s56, v198, v[60:61]
	v_add_co_u32_e32 v12, vcc, 0x1000, v10
	s_ashr_i32 s81, s80, 31
	s_nop 0
	v_addc_co_u32_e32 v13, vcc, 0, v11, vcc
	global_load_dword v106, v[6:7], off
	global_load_dword v105, v[6:7], off offset:2048
	global_load_dword v104, v[8:9], off
	global_load_dword v99, v[10:11], off
	global_load_dword v98, v[10:11], off offset:2048
	global_load_dword v97, v[12:13], off
	global_load_dword v235, v[4:5], off
	global_load_dword v234, v[4:5], off offset:2048
	s_ashr_i32 s91, s90, 31
	s_ashr_i32 s87, s86, 31
	s_ashr_i32 s83, s82, 31
	s_ashr_i32 s79, s78, 31
	s_ashr_i32 s77, s76, 31
	s_ashr_i32 s75, s74, 31
	s_ashr_i32 s73, s72, 31
	s_ashr_i32 s71, s70, 31
	s_ashr_i32 s69, s68, 31
	s_ashr_i32 s67, s66, 31
	s_ashr_i32 s65, s64, 31
	s_ashr_i32 s63, s62, 31
	s_ashr_i32 s61, s60, 31
	s_ashr_i32 s59, s58, 31
	s_ashr_i32 s57, s56, 31
	s_waitcnt vmcnt(48)
	v_swap_b32 v29, v32
	v_swap_b32 v30, v74
	v_swap_b32 v31, v132
	v_swap_b32 v34, v75
	v_swap_b32 v35, v133
	v_swap_b32 v77, v134
	v_swap_b32 v177, v228
	v_swap_b32 v178, v240
	v_swap_b32 v179, v244
	v_swap_b32 v230, v241
	v_swap_b32 v231, v245
	v_swap_b32 v243, v246
	s_nop 1
	v_mfma_f32_16x16x32_bf16 v[4:7], v[20:23], v[28:31], 0
	v_mfma_f32_16x16x32_bf16 v[8:11], v[20:23], v[32:35], 0
	v_mfma_f32_16x16x32_bf16 v[12:15], v[20:23], v[74:77], 0
	v_mfma_f32_16x16x32_bf16 v[16:19], v[20:23], v[132:135], 0
	v_mfma_f32_16x16x32_bf16 v[4:7], v[24:27], v[176:179], v[4:7]
	v_mfma_f32_16x16x32_bf16 v[8:11], v[24:27], v[228:231], v[8:11]
	v_mfma_f32_16x16x32_bf16 v[12:15], v[24:27], v[240:243], v[12:15]
	v_mfma_f32_16x16x32_bf16 v[16:19], v[24:27], v[244:247], v[16:19]
	s_nop 9
	v_swap_b32 v5, v8
	v_swap_b32 v6, v12
	v_swap_b32 v7, v16
	v_swap_b32 v10, v13
	v_swap_b32 v11, v17
	v_swap_b32 v15, v18
	ds_write_b128 v165, v[4:7] offset:256
	ds_write_b128 v165, v[8:11] offset:4352
	ds_write_b128 v165, v[12:15] offset:8448
	ds_write_b128 v165, v[16:19] offset:12544
	s_waitcnt lgkmcnt(0)
	s_barrier
; #define LAS __attribute__((address_space(3)))
; __device__ __forceinline__ float bflo(unsigned u) { return __uint_as_float(u << 16); }
; __device__ __forceinline__ float bfhi(unsigned u) { return __uint_as_float(u & 0xffff0000u); }
; #define DOT2(a_, b_, c_) __builtin_amdgcn_fdot2_f32_bf16(__builtin_bit_cast(bf16x2_t, (unsigned)(a_)), __builtin_bit_cast(bf16x2_t, (unsigned)(b_)), (c_), false)
; __global__ void __launch_bounds__(NWAVES * 64, 2) mk_fwd(Args args) {
;     ...
;                     float lw[16][2], la[16][2];
; #pragma unroll
;                     for (int t = 0; t < 16; ++t) { lw[t][0] = 0.f; lw[t][1] = 0.f; la[t][0] = 0.f; la[t][1] = 0.f; }
;                     u32x2 wvn = *(const u32x2*)(w2pl + c0), avn = *(const u32x2*)(w2pl + (size_t)32 * RW + c0);
;                     for (int ip = 0; ip < 32; ++ip) {
;                         const u32x2 wv = wvn, av = avn;
;                         { const int ipn = ip < 31 ? ip + 1 : 31; wvn = *(const u32x2*)(w2pl + (size_t)ipn * RW + c0); avn = *(const u32x2*)(w2pl + (size_t)(32 + ipn) * RW + c0); }
; #pragma unroll
;                         for (int tq = 0; tq < 4; ++tq) { const u32x4 x4 = *(LAS const u32x4*)(actP + ip * 16 + tq * 4), y4 = *(LAS const u32x4*)(actP + (32 + ip) * 16 + tq * 4);
; #pragma unroll
;                             for (int e = 0; e < 4; ++e) { lw[tq * 4 + e][0] = DOT2(x4[e], wv.x, lw[tq * 4 + e][0]); lw[tq * 4 + e][1] = DOT2(x4[e], wv.y, lw[tq * 4 + e][1]);
;                                                           la[tq * 4 + e][0] = DOT2(y4[e], av.x, la[tq * 4 + e][0]); la[tq * 4 + e][1] = DOT2(y4[e], av.y, la[tq * 4 + e][1]); } }
;                     }
;                     float pr[2], pk[2], pv[2];
;                     if (first) { if (smp) { pr[0] = shst[c0]; pr[1] = shst[c0 + 1]; pk[0] = shst[RW + c0]; pk[1] = shst[RW + c0 + 1]; pv[0] = shst[2 * RW + c0]; pv[1] = shst[2 * RW + c0 + 1]; }
;                                  else { pr[0] = pr[1] = pk[0] = pk[1] = pv[0] = pv[1] = 0.f; } }
;                     else { const unsigned ur = pur[0], uk = puk[0], uv = puv[0];
;                            pr[0] = bflo(ur); pr[1] = bfhi(ur); pk[0] = bflo(uk); pk[1] = bfhi(uk); pv[0] = bflo(uv); pv[1] = bfhi(uv); }
	ds_read_b32 v233, v194 offset:0
	ds_read_b32 v232, v194 offset:4
	ds_read_b32 v229, v194 offset:4096
	ds_read_b32 v228, v194 offset:4100
	ds_read_b32 v223, v194 offset:8192
	ds_read_b32 v222, v194 offset:8196
	ds_read_b32 v217, v194 offset:12288
	ds_read_b32 v215, v194 offset:12292
	ds_read_b32 v209, v194 offset:16384
	ds_read_b32 v208, v194 offset:16388
	ds_read_b32 v184, v194 offset:20480
	ds_read_b32 v183, v194 offset:20484
	ds_read_b32 v177, v194 offset:24576
	ds_read_b32 v176, v194 offset:24580
	ds_read_b32 v160, v194 offset:28672
	ds_read_b32 v159, v194 offset:28676
	ds_read_b32 v153, v194 offset:32768
	ds_read_b32 v152, v194 offset:32772
	ds_read_b32 v146, v194 offset:36864
	ds_read_b32 v145, v194 offset:36868
	ds_read_b32 v140, v194 offset:40960
	ds_read_b32 v139, v194 offset:40964
	ds_read_b32 v133, v194 offset:45056
	ds_read_b32 v132, v194 offset:45060
	ds_read_b32 v124, v194 offset:49152
	ds_read_b32 v123, v194 offset:49156
	ds_read_b32 v116, v194 offset:53248
	ds_read_b32 v115, v194 offset:53252
	ds_read_b32 v108, v194 offset:57344
	ds_read_b32 v107, v194 offset:57348
	ds_read_b32 v101, v194 offset:61440
	ds_read_b32 v100, v194 offset:61444
	ds_read_b32 v237, v195 offset:0
	ds_read_b32 v236, v195 offset:4
	ds_read_b32 v231, v195 offset:4096
	ds_read_b32 v230, v195 offset:4100
	ds_read_b32 v226, v195 offset:8192
	ds_read_b32 v225, v195 offset:8196
	ds_read_b32 v219, v195 offset:12288
	ds_read_b32 v218, v195 offset:12292
	ds_read_b32 v212, v195 offset:16384
	ds_read_b32 v211, v195 offset:16388
	ds_read_b32 v186, v195 offset:20480
	ds_read_b32 v185, v195 offset:20484
	ds_read_b32 v179, v195 offset:24576
	ds_read_b32 v178, v195 offset:24580
	ds_read_b32 v172, v195 offset:28672
	ds_read_b32 v163, v195 offset:28676
	ds_read_b32 v157, v195 offset:32768
	ds_read_b32 v154, v195 offset:32772
	ds_read_b32 v150, v195 offset:36864
	ds_read_b32 v149, v195 offset:36868
	ds_read_b32 v122, v195 offset:40960
	ds_read_b32 v141, v195 offset:40964
	ds_read_b32 v135, v195 offset:45056
	ds_read_b32 v134, v195 offset:45060
	ds_read_b32 v128, v195 offset:49152
	ds_read_b32 v126, v195 offset:49156
	ds_read_b32 v119, v195 offset:53248
	ds_read_b32 v118, v195 offset:53252
	ds_read_b32 v112, v195 offset:57344
	ds_read_b32 v111, v195 offset:57348
	ds_read_b32 v103, v195 offset:61440
	ds_read_b32 v102, v195 offset:61444
	s_waitcnt vmcnt(0) lgkmcnt(0)
	s_mov_b64 s[92:93], -1
	s_and_b64 vcc, exec, s[88:89]
	s_cbranch_vccz .LBB0_463
	v_lshlrev_b32_e32 v86, 16, v81
	v_and_b32_e32 v87, 0xffff0000, v81
	v_lshlrev_b32_e32 v84, 16, v80
	v_and_b32_e32 v85, 0xffff0000, v80
	v_lshlrev_b32_e32 v82, 16, v227
	v_and_b32_e32 v83, 0xffff0000, v227
	s_mov_b64 s[92:93], 0

; __global__ void __launch_bounds__(NWAVES * 64, 2) mk_fwd(Args args) {
;     ...
;                 const float* gq = args.in[23] + (size_t)l * QL; const float* gkv = args.in[24] + (size_t)l * KVL; const float* gkr = args.in[31] + (size_t)l * ROPE;
;                 const float* cw = args.in[32] + (size_t)l * 3 * CONVD; const float* cb = args.in[33] + (size_t)l * CONVD;
;                 for (int m = gw; m < M; m += ngw) {
;                     const bool smp = m >= MP;
;                     const int b = smp ? ((m - MP) >> 5) : (m >> 12), t = smp ? ((m - MP) & 31) : (m & 4095);
;                     const int pos = smp ? PAST + t : t;
;                     const int T = smp ? DS : SEQ;
;                     const size_t lrow = smp ? (size_t)MP + (size_t)b * SKEYS + PAST + t : (size_t)m;
;                     float* lat_out = smp ? out + O_LATS + ((size_t)(l * DB + b) * DS + t) * KVL : out + O_LATP + ((size_t)(l * NB + b) * SEQ + t) * KVL;
;                     float* kr_out = smp ? out + O_KRS + ((size_t)(l * DB + b) * DS + t) * ROPE : out + O_KRP + ((size_t)(l * NB + b) * SEQ + t) * ROPE;
;                     const bf16_t* prow = proj + (size_t)m * NPAD;
;                     const u32x4 rq0 = *(const u32x4*)(prow + C_CQ + lane * 8), rq1 = *(const u32x4*)(prow + C_CQ + 512 + lane * 8), rkv = *(const u32x4*)(prow + C_CKV + lane * 8);
;                     const bf16_t rkr = prow[C_KR + lane];
.LBB0_498:
	v_readlane_b32 s36, v252, 4
	s_lshl_b64 s[2:3], s[48:49], 2
	v_readlane_b32 s42, v252, 10
	v_readlane_b32 s37, v252, 5
	v_readlane_b32 s43, v252, 11
	s_add_u32 s36, s42, s2
	v_readlane_b32 s38, v252, 6
	s_addc_u32 s37, s43, s3
	s_ashr_i32 s2, s10, 6
	s_lshl_b32 s3, s1, 3
	s_add_i32 s38, s3, s2
	s_add_i32 s38, s38, 0x700
	s_and_b32 s38, s38, 0x7ff
	s_lshl_b32 s50, s0, 3
	s_add_u32 s2, s52, 0x4a700000
	s_addc_u32 s3, s53, 0
	v_writelane_b32 v254, s2, 62
	v_and_b32_e32 v108, 63, v109
	v_readlane_b32 s39, v252, 7
	v_writelane_b32 v254, s3, 63
	s_add_u32 s2, s52, 0x4d800000
	s_addc_u32 s3, s53, 0
	v_writelane_b32 v255, s2, 0
	s_cmpk_gt_i32 s38, 0x41ff
	v_readlane_b32 s40, v252, 8
	v_writelane_b32 v255, s3, 1
	v_readlane_b32 s41, v252, 9
	s_waitcnt vmcnt(0) lgkmcnt(0)
	s_barrier
	s_cbranch_scc1 .LBB0_597
	s_add_u32 s52, s52, 0x100000
	v_readlane_b32 s56, v252, 4
	s_addc_u32 s53, s53, 0
	s_lshl_b64 s[2:3], s[54:55], 2
	v_readlane_b32 s58, v252, 6
	v_readlane_b32 s59, v252, 7
	s_add_u32 s4, s58, s2
	v_readlane_b32 s40, v254, 54
	s_addc_u32 s5, s59, s3
	s_mul_i32 s6, s40, 0x3000
	v_readlane_b32 s57, v252, 5
	v_readlane_b32 s60, v252, 8
	v_readlane_b32 s61, v252, 9
	v_readlane_b32 s62, v252, 10
	v_readlane_b32 s63, v252, 11
	s_add_u32 s6, s56, s6
	v_readlane_b32 s41, v254, 55
	s_addc_u32 s7, s57, 0
	v_readlane_b32 s56, v252, 18
	s_lshl_b64 s[8:9], s[40:41], 8
	v_readlane_b32 s70, v252, 32
	v_readlane_b32 s71, v252, 33
	s_add_u32 s8, s70, s8
	s_addc_u32 s9, s71, s9
	s_lshl_b64 s[54:55], s[40:41], 11
	v_readlane_b32 s57, v252, 19
	v_readlane_b32 s58, v252, 20
	v_readlane_b32 s59, v252, 21
	v_readlane_b32 s60, v252, 22
	v_readlane_b32 s61, v252, 23
	v_readlane_b32 s62, v252, 24
	v_readlane_b32 s63, v252, 25
	v_readlane_b32 s64, v252, 26
	v_readlane_b32 s65, v252, 27
	v_readlane_b32 s66, v252, 28
	v_readlane_b32 s67, v252, 29
	v_readlane_b32 s68, v252, 30
	v_readlane_b32 s69, v252, 31
	s_add_u32 s54, s56, s54
	s_addc_u32 s55, s57, s55
	v_readlane_b32 s56, v252, 52
	v_readlane_b32 s70, v253, 2
	v_readlane_b32 s71, v253, 3
	s_add_u32 s2, s70, s2
	s_addc_u32 s3, s71, s3
	s_add_u32 s19, s36, 0x10800000
	s_addc_u32 s72, s37, 0
	s_lshl_b32 s73, s40, 2
	s_add_u32 s74, s36, 0x15229000
	s_addc_u32 s75, s37, 0
	s_lshl_b32 s76, s40, 4
	s_add_u32 s77, s36, 0x14800000
	s_addc_u32 s78, s37, 0
	s_add_u32 s79, s36, 0x15429000
	v_cmp_lt_i32_e32 vcc, v192, v191
	s_addc_u32 s96, s37, 0
	s_add_u32 s97, s36, 0x15219000
	v_cndmask_b32_e32 v8, v190, v192, vcc
	v_cmp_lt_i32_e32 vcc, v193, v191
	v_xor_b32_e32 v2, 4, v190
	s_addc_u32 s40, s37, 0
	v_cndmask_b32_e32 v9, v190, v193, vcc
	v_cmp_lt_i32_e32 vcc, v202, v191
	s_add_u32 s41, s36, 0x15ccd000
	s_addc_u32 s42, s37, 0
	v_cndmask_b32_e32 v10, v190, v202, vcc
	v_cmp_lt_i32_e32 vcc, v2, v191
	s_ashr_i32 s39, s38, 31
	s_ashr_i32 s51, s50, 31
	v_cndmask_b32_e32 v11, v190, v2, vcc
	v_lshlrev_b32_e32 v2, 5, v108
	v_lshl_add_u64 v[110:111], s[2:3], 0, v[2:3]
	v_lshl_add_u64 v[118:119], s[6:7], 0, v[2:3]
	s_lshl_b64 s[2:3], s[38:39], 11
	v_readlane_b32 s6, v252, 12
	v_readlane_b32 s7, v252, 13
	s_add_u32 s2, s6, s2
	v_lshl_add_u64 v[112:113], s[54:55], 0, v[2:3]
	v_lshlrev_b32_e32 v4, 4, v108
	v_mov_b32_e32 v5, v3
	v_lshl_add_u64 v[116:117], s[4:5], 0, v[2:3]
	s_addc_u32 s3, s7, s3
	s_lshl_b64 s[54:55], s[50:51], 11
	s_mul_i32 s5, s38, 0x5e00
	v_lshl_add_u64 v[120:121], s[2:3], 0, v[4:5]
	s_mul_hi_i32 s4, s38, 0x5e00
	s_add_u32 s2, s6, s5
	s_addc_u32 s3, s7, s4
	v_lshl_add_u64 v[122:123], s[2:3], 0, v[4:5]
	s_lshl_b64 s[2:3], s[38:39], 13
	s_add_u32 s2, s6, s2
	v_readlane_b32 s57, v252, 53
	s_addc_u32 s3, s7, s3
	v_lshl_add_u64 v[124:125], s[2:3], 0, v[4:5]
	s_lshl_b64 s[56:57], s[50:51], 13
	v_readlane_b32 s2, v254, 31
	s_add_u32 s2, s2, s5
	v_readlane_b32 s3, v254, 32
	s_addc_u32 s3, s3, s4
	v_readlane_b32 s4, v254, 62
	v_readlane_b32 s5, v254, 63
	v_cmp_lt_i32_e32 vcc, v196, v191
	v_readlane_b32 s58, v252, 54
	v_lshl_add_u64 v[128:129], s[4:5], 0, v[4:5]
	v_readlane_b32 s4, v255, 0
	v_lshlrev_b32_e32 v4, 1, v108
	v_readlane_b32 s5, v255, 1
	v_cndmask_b32_e32 v12, v190, v196, vcc
	v_cmp_lt_i32_e32 vcc, v197, v191
	v_lshl_add_u64 v[130:131], s[4:5], 0, v[4:5]
	s_mov_b64 s[4:5], 0x1000
	v_lshl_add_u64 v[132:133], v[118:119], 0, s[4:5]
	s_mov_b64 s[4:5], 0x2000
	v_lshl_add_u64 v[134:135], v[118:119], 0, s[4:5]
	s_mov_b64 s[4:5], 0x800
	v_lshl_add_u64 v[136:137], v[118:119], 0, s[4:5]
	s_mov_b64 s[4:5], 0x1800
	v_readlane_b32 s59, v252, 55
	v_readlane_b32 s60, v252, 56
	v_readlane_b32 s61, v252, 57
	v_cndmask_b32_e32 v13, v190, v197, vcc
	v_lshlrev_b32_e32 v6, 2, v108
	v_mov_b32_e32 v7, v3
	v_lshl_add_u64 v[138:139], v[118:119], 0, s[4:5]
	s_mov_b64 s[4:5], 0x2800
	v_lshl_add_u64 v[114:115], s[8:9], 0, v[6:7]
	v_lshlrev_b32_e32 v126, 3, v108
	v_lshlrev_b32_e32 v174, 2, v8
	v_lshlrev_b32_e32 v175, 2, v9
	v_lshlrev_b32_e32 v176, 2, v10
	v_lshlrev_b32_e32 v177, 2, v11
	v_lshlrev_b32_e32 v178, 2, v12
	v_lshlrev_b32_e32 v179, 2, v13
	v_lshl_add_u64 v[140:141], v[118:119], 0, s[4:5]
	v_lshl_add_u64 v[142:143], s[2:3], 0, v[4:5]
	s_mul_hi_i32 s59, s50, 0x5e00
	s_mul_i32 s58, s50, 0x5e00
	v_lshlrev_b32_e32 v180, 2, v108
	v_cmp_gt_u32_e64 s[2:3], 32, v108
	s_mov_b64 s[60:61], s[38:39]
	v_readlane_b32 s62, v252, 58
	v_readlane_b32 s63, v252, 59
	v_readlane_b32 s64, v252, 60
	v_readlane_b32 s65, v252, 61
	v_readlane_b32 s66, v252, 62
	v_readlane_b32 s67, v252, 63
	v_readlane_b32 s68, v253, 0
	v_readlane_b32 s69, v253, 1
	s_branch .LBB0_501

; __device__ __forceinline__ unsigned cvtpk(float lo, float hi) { unsigned r; asm volatile("v_cvt_pk_bf16_f32 %0, %1, %2" : "=v"(r) : "v"(lo), "v"(hi)); return r; }
; __device__ __forceinline__ bf16_t f2bf(float f) { return (bf16_t)(cvtpk(f, 0.f) & 0xffffu); }
; __global__ void __launch_bounds__(NWAVES * 64, 2) mk_fwd(Args args) {
;     ...
;             {
;                 const float* clat = args.in[4] + (size_t)l * DB * PAST * KVL; const float* ckr = args.in[5] + (size_t)l * DB * PAST * ROPE;
;                 if (G == 256) {
;                     for (int r0 = gw; r0 < DB * PAST; r0 += 8 * 2048) {
;                         f32x4 a0[8], a1[8]; float kx[8];
; #pragma unroll
;                         for (int q = 0; q < 8; ++q) { const int r = r0 + q * 2048;
;                             a0[q] = *(const f32x4*)(clat + (size_t)r * KVL + lane * 8); a1[q] = *(const f32x4*)(clat + (size_t)r * KVL + lane * 8 + 4); kx[q] = ckr[(size_t)r * ROPE + lane]; }
; #pragma unroll
;                         for (int q = 0; q < 8; ++q) { const int r = r0 + q * 2048;
;                             const int b = r >> 11, p = r & 2047; const size_t lrow = (size_t)MP + (size_t)b * SKEYS + p;
;                             u32x4 w; w.x = cvtpk(a0[q].x, a0[q].y); w.y = cvtpk(a0[q].z, a0[q].w); w.z = cvtpk(a1[q].x, a1[q].y); w.w = cvtpk(a1[q].z, a1[q].w);
;                             *(u32x4*)(latall + lrow * KVL + lane * 8) = w;
;                             Krb[lrow * ROPE + lane] = f2bf(kx[q]); }
;                     }
.LBB0_597:
	s_add_i32 s38, s38, 0x100
	s_and_b32 s38, s38, 0x7ff
	v_readlane_b32 s2, v254, 54
	v_readlane_b32 s3, v254, 55
	s_lshl_b64 s[64:65], s[2:3], 26
	s_lshl_b64 s[66:67], s[2:3], 23
	s_cmp_lt_i32 s38, 0x8000
	s_cselect_b64 s[2:3], -1, 0
	v_cndmask_b32_e64 v2, 0, 1, s[2:3]
	s_cmpk_eq_i32 s0, 0x100
	s_mov_b64 s[4:5], -1
	v_cmp_ne_u32_e64 s[2:3], 1, v2
	s_cbranch_scc1 .LBB0_602
	s_and_b64 vcc, exec, s[2:3]
	s_cbranch_vccnz .LBB0_601
	v_readlane_b32 s4, v254, 62
	v_lshlrev_b32_e32 v2, 4, v108
	v_readlane_b32 s5, v254, 63
	s_ashr_i32 s39, s38, 31
	v_readlane_b32 s68, v252, 36
	v_lshl_add_u64 v[4:5], s[4:5], 0, v[2:3]
	v_readlane_b32 s4, v255, 0
	v_lshlrev_b32_e32 v2, 1, v108
	v_readlane_b32 s5, v255, 1
	v_readlane_b32 s69, v252, 37
	v_readlane_b32 s70, v252, 38
	v_lshl_add_u64 v[6:7], s[4:5], 0, v[2:3]
	s_lshl_b64 s[4:5], s[38:39], 8
	v_readlane_b32 s71, v252, 39
	v_readlane_b32 s72, v252, 40
	v_readlane_b32 s73, v252, 41
	v_readlane_b32 s74, v252, 42
	v_readlane_b32 s75, v252, 43
	v_readlane_b32 s76, v252, 44
	v_readlane_b32 s77, v252, 45
	s_add_u32 s4, s66, s4
	v_readlane_b32 s78, v252, 46
	v_readlane_b32 s79, v252, 47
	v_readlane_b32 s80, v252, 48
	v_readlane_b32 s81, v252, 49
	v_readlane_b32 s82, v252, 50
	v_readlane_b32 s83, v252, 51
	s_mov_b64 s[68:69], s[76:77]
	s_addc_u32 s5, s67, s5
	s_mov_b64 s[70:71], s[78:79]
	s_add_u32 s4, s70, s4
	v_lshlrev_b32_e32 v2, 2, v108
	s_addc_u32 s5, s71, s5
	s_ashr_i32 s51, s50, 31
	v_lshl_add_u64 v[8:9], s[4:5], 0, v[2:3]
	s_lshl_b64 s[4:5], s[50:51], 8
	s_lshl_b64 s[6:7], s[38:39], 11
	s_add_u32 s6, s64, s6
	s_addc_u32 s7, s65, s7
	v_readlane_b32 s8, v254, 33
	s_add_u32 s6, s8, s6
	v_readlane_b32 s8, v254, 34
	v_lshlrev_b32_e32 v2, 5, v108
	s_addc_u32 s7, s8, s7
	v_lshl_add_u64 v[10:11], s[6:7], 0, v[2:3]
	s_lshl_b64 s[6:7], s[50:51], 11
	s_mov_b32 s10, s38
	s_mov_b64 s[72:73], s[80:81]
	s_mov_b64 s[74:75], s[82:83]
